# cache policy: ln1 reads the once-used Y rows with non-temporal loads
# baseline (speedup 1.0000x reference)
.LBB0_589:
	v_add_u32_e32 v0, 0xfffff000, v18
	v_lshrrev_b32_e32 v0, 12, v0
	v_lshl_add_u64 v[74:75], s[8:9], 0, v[32:33]
	v_add_u32_e32 v19, 1, v0
	v_add_co_u32_e32 v0, vcc, 0x1874b000, v74
	v_mov_b64_e32 v[44:45], s[12:13]
	s_nop 0
	v_addc_co_u32_e32 v1, vcc, 0, v75, vcc
	v_cmp_lt_i32_e32 vcc, s18, v18
	v_lshl_add_u64 v[110:111], s[8:9], 0, v[34:35]
	v_mov_b32_e32 v37, v16
	v_cndmask_b32_e32 v19, 0, v19, vcc
	v_add_u32_e32 v19, s60, v19
	v_mad_u64_u32 v[44:45], s[16:17], v19, s41, v[44:45]
	s_mov_b64 s[16:17], 0x4000
	s_nop 0
	v_lshl_add_u64 v[72:73], v[44:45], 0, s[16:17]
	s_mov_b64 s[16:17], 0x8000
	v_lshl_add_u64 v[52:53], v[44:45], 0, s[16:17]
	s_mov_b64 s[16:17], 0x6000
	v_lshl_add_u64 v[54:55], v[44:45], 0, s[16:17]
	s_mov_b32 s16, 0x1274b000
	v_add_co_u32_e32 v46, vcc, s16, v110
	v_lshl_add_u64 v[44:45], v[110:111], 0, s[20:21]
	s_nop 0
	v_addc_co_u32_e32 v47, vcc, 0, v111, vcc
	global_load_dwordx4 v[12:15], v[0:1], off offset:512 nt
	global_load_dwordx4 v[8:11], v[0:1], off offset:1536 nt
	global_load_dwordx4 v[4:7], v[0:1], off offset:2560 nt
	s_nop 0
	global_load_dwordx4 v[0:3], v[0:1], off offset:3584 nt
	s_nop 0
	global_load_dwordx4 v[48:51], v[46:47], off offset:512
	global_load_dwordx4 v[56:59], v[44:45], off offset:16
	v_lshl_add_u64 v[44:45], v[72:73], 0, v[36:37]
	global_load_dwordx4 v[60:63], v[44:45], off
	global_load_dwordx4 v[64:67], v[44:45], off offset:16
	s_mov_b64 s[16:17], 0x1274ba00
	v_lshl_add_u64 v[44:45], v[110:111], 0, s[16:17]
	v_mov_b32_e32 v39, v16
	s_mov_b64 s[16:17], 0x1274c200
	global_load_dwordx4 v[68:71], v[46:47], off offset:2560
	global_load_dwordx4 v[82:85], v[44:45], off offset:16
	v_lshl_add_u64 v[44:45], v[72:73], 0, v[38:39]
	v_lshl_add_u64 v[98:99], v[110:111], 0, s[16:17]
	s_mov_b32 s16, 0x1274c000
	global_load_dwordx4 v[86:89], v[44:45], off
	global_load_dwordx4 v[90:93], v[44:45], off offset:16
	v_add_co_u32_e32 v44, vcc, s16, v110
	v_mov_b32_e32 v41, v16
	s_mov_b64 s[16:17], 0x1274ca00
	v_mov_b32_e32 v43, v16
	v_addc_co_u32_e32 v45, vcc, 0, v111, vcc
	v_lshl_add_u64 v[106:107], v[72:73], 0, v[40:41]
	v_lshl_add_u64 v[114:115], v[110:111], 0, s[16:17]
	v_lshl_add_u64 v[72:73], v[72:73], 0, v[42:43]
	global_load_dwordx4 v[94:97], v[44:45], off offset:512
	s_nop 0
	global_load_dwordx4 v[98:101], v[98:99], off offset:16
	s_nop 0
	global_load_dwordx4 v[102:105], v[106:107], off
	s_nop 0
	global_load_dwordx4 v[106:109], v[106:107], off offset:16
	s_nop 0
	global_load_dwordx4 v[110:113], v[44:45], off offset:2560
	s_nop 0
	global_load_dwordx4 v[114:117], v[114:115], off offset:16
	s_nop 0
	global_load_dwordx4 v[118:121], v[72:73], off
	global_load_dwordx4 v[122:125], v[72:73], off offset:16
	v_lshl_add_u64 v[138:139], v[54:55], 0, v[36:37]
	s_mov_b32 s16, 0x1b74b000
	v_add_u32_e32 v18, s72, v18
	v_lshl_add_u64 v[32:33], v[32:33], 0, s[0:1]
	v_lshl_add_u64 v[34:35], v[34:35], 0, s[70:71]
	s_waitcnt vmcnt(0)
	v_lshlrev_b32_e32 v134, 16, v14
	v_and_b32_e32 v135, 0xffff0000, v14
	v_lshlrev_b32_e32 v14, 16, v15
	v_and_b32_e32 v15, 0xffff0000, v15
	v_and_b32_e32 v73, 0xffff0000, v2
	v_lshlrev_b32_e32 v72, 16, v2
	v_pk_mul_f32 v[14:15], v[66:67], v[14:15]
	v_pk_mul_f32 v[64:65], v[64:65], v[134:135]
	v_pk_fma_f32 v[58:59], v[58:59], s[86:87], v[14:15] op_sel_hi:[1,0,1]
	v_lshlrev_b32_e32 v14, 16, v12
	v_and_b32_e32 v15, 0xffff0000, v12
	v_pk_mul_f32 v[14:15], v[60:61], v[14:15]
	v_pk_fma_f32 v[56:57], v[56:57], s[86:87], v[64:65] op_sel_hi:[1,0,1]
	v_pk_fma_f32 v[66:67], v[48:49], s[86:87], v[14:15] op_sel_hi:[1,0,1]
	v_lshl_add_u64 v[64:65], v[52:53], 0, v[38:39]
	v_add_f32_e32 v12, 0, v66
	v_add_f32_e32 v14, v67, v12
	v_lshlrev_b32_e32 v12, 16, v13
	v_and_b32_e32 v13, 0xffff0000, v13
	v_pk_mul_f32 v[12:13], v[62:63], v[12:13]
	v_lshl_add_u64 v[60:61], v[54:55], 0, v[38:39]
	v_pk_fma_f32 v[62:63], v[50:51], s[86:87], v[12:13] op_sel_hi:[1,0,1]
	v_pk_mul_f32 v[72:73], v[122:123], v[72:73]
	v_add_f32_e32 v12, v62, v14
	v_add_f32_e32 v12, v63, v12
	v_add_f32_e32 v12, v56, v12
	v_pk_fma_f32 v[142:143], v[114:115], s[86:87], v[72:73] op_sel_hi:[1,0,1]
	v_and_b32_e32 v73, 0xffff0000, v3
	v_lshlrev_b32_e32 v72, 16, v3
	v_add_f32_e32 v12, v57, v12
	v_pk_mul_f32 v[2:3], v[124:125], v[72:73]
	v_lshl_add_u64 v[72:73], v[52:53], 0, v[36:37]
	v_add_f32_e32 v12, v58, v12
	v_pk_fma_f32 v[2:3], v[116:117], s[86:87], v[2:3] op_sel_hi:[1,0,1]
	global_load_dwordx4 v[114:117], v[20:21], off
	global_load_dwordx4 v[122:125], v[20:21], off offset:16
	global_load_dwordx4 v[126:129], v[22:23], off
	global_load_dwordx4 v[130:133], v[22:23], off offset:16
	v_add_f32_e32 v19, v59, v12
	global_load_dwordx4 v[12:15], v[72:73], off offset:16
	global_load_dwordx4 v[48:51], v[72:73], off
	global_load_dwordx4 v[134:137], v[138:139], off offset:16
	s_nop 0
	global_load_dwordx4 v[138:141], v[138:139], off
	s_waitcnt vmcnt(3)
	v_pk_add_f32 v[150:151], v[14:15], 1.0 op_sel_hi:[1,0]
	v_lshlrev_b32_e32 v14, 16, v8
	v_and_b32_e32 v15, 0xffff0000, v8
	v_pk_mul_f32 v[14:15], v[86:87], v[14:15]
	v_pk_add_f32 v[148:149], v[12:13], 1.0 op_sel_hi:[1,0]
	v_pk_fma_f32 v[14:15], v[68:69], s[86:87], v[14:15] op_sel_hi:[1,0,1]
	v_lshlrev_b32_e32 v12, 16, v10
	v_add_f32_e32 v8, v14, v19
	v_add_f32_e32 v19, v15, v8
	v_lshlrev_b32_e32 v8, 16, v9
	v_and_b32_e32 v9, 0xffff0000, v9
	v_pk_mul_f32 v[8:9], v[88:89], v[8:9]
	v_and_b32_e32 v13, 0xffff0000, v10
	v_pk_fma_f32 v[8:9], v[70:71], s[86:87], v[8:9] op_sel_hi:[1,0,1]
	v_pk_mul_f32 v[12:13], v[90:91], v[12:13]
	v_add_f32_e32 v19, v8, v19
	v_pk_fma_f32 v[12:13], v[82:83], s[86:87], v[12:13] op_sel_hi:[1,0,1]
	v_lshlrev_b32_e32 v10, 16, v11
	v_and_b32_e32 v11, 0xffff0000, v11
	v_add_f32_e32 v19, v9, v19
	v_lshlrev_b32_e32 v68, 16, v6
	v_and_b32_e32 v69, 0xffff0000, v6
	v_lshlrev_b32_e32 v6, 16, v7
	v_and_b32_e32 v7, 0xffff0000, v7
	v_pk_mul_f32 v[10:11], v[92:93], v[10:11]
	v_add_f32_e32 v19, v12, v19
	v_pk_mul_f32 v[6:7], v[108:109], v[6:7]
	v_pk_fma_f32 v[10:11], v[84:85], s[86:87], v[10:11] op_sel_hi:[1,0,1]
	v_add_f32_e32 v19, v13, v19
	v_pk_fma_f32 v[84:85], v[100:101], s[86:87], v[6:7] op_sel_hi:[1,0,1]
	v_lshlrev_b32_e32 v6, 16, v4
	v_and_b32_e32 v7, 0xffff0000, v4
	v_add_f32_e32 v19, v10, v19
	v_pk_mul_f32 v[6:7], v[102:103], v[6:7]
	v_add_f32_e32 v19, v11, v19
	v_pk_fma_f32 v[86:87], v[94:95], s[86:87], v[6:7] op_sel_hi:[1,0,1]
	v_pk_mul_f32 v[68:69], v[106:107], v[68:69]
	v_add_f32_e32 v4, v86, v19
	v_add_f32_e32 v6, v87, v4
	v_lshlrev_b32_e32 v4, 16, v5
	v_and_b32_e32 v5, 0xffff0000, v5
	v_pk_mul_f32 v[4:5], v[104:105], v[4:5]
	v_pk_fma_f32 v[82:83], v[98:99], s[86:87], v[68:69] op_sel_hi:[1,0,1]
	v_pk_fma_f32 v[88:89], v[96:97], s[86:87], v[4:5] op_sel_hi:[1,0,1]
	s_waitcnt vmcnt(2)
	v_pk_add_f32 v[146:147], v[50:51], 1.0 op_sel_hi:[1,0]
	v_add_f32_e32 v4, v88, v6
	v_add_f32_e32 v4, v89, v4
	v_add_f32_e32 v4, v82, v4
	v_lshl_add_u64 v[50:51], v[52:53], 0, v[40:41]
	v_add_f32_e32 v4, v83, v4
	v_lshl_add_u64 v[6:7], v[52:53], 0, v[42:43]
	v_lshlrev_b32_e32 v52, 16, v0
	v_and_b32_e32 v53, 0xffff0000, v0
	v_add_f32_e32 v4, v84, v4
	v_pk_mul_f32 v[52:53], v[118:119], v[52:53]
	v_add_f32_e32 v19, v85, v4
	v_pk_fma_f32 v[52:53], v[110:111], s[86:87], v[52:53] op_sel_hi:[1,0,1]
	v_pk_add_f32 v[144:145], v[48:49], 1.0 op_sel_hi:[1,0]
	v_add_f32_e32 v0, v52, v19
	v_add_f32_e32 v19, v53, v0
	v_lshlrev_b32_e32 v0, 16, v1
	v_and_b32_e32 v1, 0xffff0000, v1
	v_pk_mul_f32 v[0:1], v[120:121], v[0:1]
	v_lshl_add_u64 v[48:49], v[54:55], 0, v[40:41]
	v_pk_fma_f32 v[0:1], v[112:113], s[86:87], v[0:1] op_sel_hi:[1,0,1]
	v_lshl_add_u64 v[4:5], v[54:55], 0, v[42:43]
	v_add_f32_e32 v19, v0, v19
	v_add_f32_e32 v19, v1, v19
	v_add_f32_e32 v19, v142, v19
	v_add_f32_e32 v19, v143, v19
	v_add_f32_e32 v19, v2, v19
	v_add_f32_e32 v19, v3, v19
	s_waitcnt lgkmcnt(0)
	v_mov_b32_e32 v37, v19
	s_nop 1
	v_permlane32_swap_b32_e32 v37, v19
	v_add_f32_e32 v19, v19, v37
	v_mov_b32_e32 v37, v19
	s_nop 1
	v_permlane16_swap_b32_e32 v37, v19
	v_add_f32_e32 v19, v19, v37
	s_nop 1
	v_add_f32_dpp v19, v19, v19 row_ror:8 row_mask:0xf bank_mask:0xf
	s_nop 1
	v_add_f32_dpp v19, v19, v19 row_ror:4 row_mask:0xf bank_mask:0xf
	s_nop 1
	v_add_f32_dpp v19, v19, v19 row_ror:2 row_mask:0xf bank_mask:0xf
	s_nop 1
	v_add_f32_dpp v19, v19, v19 row_ror:1 row_mask:0xf bank_mask:0xf
	v_mul_f32_e32 v90, 0x3a000000, v19
	v_pk_add_f32 v[92:93], v[66:67], v[90:91] op_sel_hi:[1,0] neg_lo:[0,1] neg_hi:[0,1]
	v_pk_add_f32 v[96:97], v[62:63], v[90:91] op_sel_hi:[1,0] neg_lo:[0,1] neg_hi:[0,1]
	v_pk_mul_f32 v[94:95], v[92:93], v[92:93]
	v_pk_mul_f32 v[98:99], v[96:97], v[96:97]
	v_add_f32_e32 v19, v94, v95
	v_pk_add_f32 v[100:101], v[56:57], v[90:91] op_sel_hi:[1,0] neg_lo:[0,1] neg_hi:[0,1]
	v_add_f32_e32 v19, v98, v19
	v_pk_mul_f32 v[102:103], v[100:101], v[100:101]
	v_add_f32_e32 v19, v99, v19
	v_pk_add_f32 v[104:105], v[58:59], v[90:91] op_sel_hi:[1,0] neg_lo:[0,1] neg_hi:[0,1]
	v_add_f32_e32 v19, v102, v19
	v_pk_mul_f32 v[106:107], v[104:105], v[104:105]
	v_add_f32_e32 v19, v103, v19
	v_pk_add_f32 v[72:73], v[14:15], v[90:91] op_sel_hi:[1,0] neg_lo:[0,1] neg_hi:[0,1]
	v_add_f32_e32 v19, v106, v19
	v_pk_mul_f32 v[108:109], v[72:73], v[72:73]
	v_add_f32_e32 v19, v107, v19
	v_pk_add_f32 v[68:69], v[8:9], v[90:91] op_sel_hi:[1,0] neg_lo:[0,1] neg_hi:[0,1]
	v_add_f32_e32 v19, v108, v19
	v_pk_mul_f32 v[110:111], v[68:69], v[68:69]
	v_add_f32_e32 v19, v109, v19
	v_pk_add_f32 v[70:71], v[12:13], v[90:91] op_sel_hi:[1,0] neg_lo:[0,1] neg_hi:[0,1]
	v_add_f32_e32 v19, v110, v19
	v_pk_mul_f32 v[112:113], v[70:71], v[70:71]
	v_add_f32_e32 v19, v111, v19
	v_pk_add_f32 v[66:67], v[10:11], v[90:91] op_sel_hi:[1,0] neg_lo:[0,1] neg_hi:[0,1]
	v_add_f32_e32 v19, v112, v19
	v_pk_mul_f32 v[118:119], v[66:67], v[66:67]
	v_add_f32_e32 v19, v113, v19
	v_pk_add_f32 v[62:63], v[86:87], v[90:91] op_sel_hi:[1,0] neg_lo:[0,1] neg_hi:[0,1]
	v_add_f32_e32 v19, v118, v19
	v_pk_mul_f32 v[86:87], v[62:63], v[62:63]
	v_add_f32_e32 v19, v119, v19
	v_pk_add_f32 v[56:57], v[88:89], v[90:91] op_sel_hi:[1,0] neg_lo:[0,1] neg_hi:[0,1]
	v_add_f32_e32 v19, v86, v19
	v_pk_mul_f32 v[88:89], v[56:57], v[56:57]
	v_add_f32_e32 v19, v87, v19
	v_pk_add_f32 v[58:59], v[82:83], v[90:91] op_sel_hi:[1,0] neg_lo:[0,1] neg_hi:[0,1]
	v_add_f32_e32 v19, v88, v19
	v_pk_mul_f32 v[82:83], v[58:59], v[58:59]
	v_add_f32_e32 v19, v89, v19
	v_pk_add_f32 v[54:55], v[84:85], v[90:91] op_sel_hi:[1,0] neg_lo:[0,1] neg_hi:[0,1]
	v_add_f32_e32 v19, v82, v19
	v_pk_mul_f32 v[84:85], v[54:55], v[54:55]
	v_add_f32_e32 v19, v83, v19
	v_pk_add_f32 v[14:15], v[52:53], v[90:91] op_sel_hi:[1,0] neg_lo:[0,1] neg_hi:[0,1]
	v_add_f32_e32 v19, v84, v19
	v_pk_mul_f32 v[52:53], v[14:15], v[14:15]
	v_add_f32_e32 v19, v85, v19
	v_pk_add_f32 v[10:11], v[0:1], v[90:91] op_sel_hi:[1,0] neg_lo:[0,1] neg_hi:[0,1]
	v_add_f32_e32 v19, v52, v19
	v_pk_mul_f32 v[0:1], v[10:11], v[10:11]
	v_add_f32_e32 v19, v53, v19
	v_pk_add_f32 v[12:13], v[142:143], v[90:91] op_sel_hi:[1,0] neg_lo:[0,1] neg_hi:[0,1]
	v_add_f32_e32 v0, v0, v19
	v_pk_mul_f32 v[120:121], v[12:13], v[12:13]
	v_add_f32_e32 v0, v1, v0
	v_pk_add_f32 v[8:9], v[2:3], v[90:91] op_sel_hi:[1,0] neg_lo:[0,1] neg_hi:[0,1]
	v_add_f32_e32 v0, v120, v0
	v_pk_mul_f32 v[2:3], v[8:9], v[8:9]
	v_add_f32_e32 v0, v121, v0
	v_add_f32_e32 v0, v2, v0
	v_add_f32_e32 v0, v3, v0
	s_waitcnt lgkmcnt(0)
	v_mov_b32_e32 v1, v0
	s_nop 1
	v_permlane32_swap_b32_e32 v1, v0
	v_add_f32_e32 v0, v0, v1
	v_mov_b32_e32 v1, v0
	s_nop 1
	v_permlane16_swap_b32_e32 v1, v0
	v_add_f32_e32 v0, v0, v1
	s_nop 1
	v_add_f32_dpp v0, v0, v0 row_ror:8 row_mask:0xf bank_mask:0xf
	s_nop 1
	v_add_f32_dpp v0, v0, v0 row_ror:4 row_mask:0xf bank_mask:0xf
	s_nop 1
	v_add_f32_dpp v0, v0, v0 row_ror:2 row_mask:0xf bank_mask:0xf
	s_nop 1
	v_add_f32_dpp v0, v0, v0 row_ror:1 row_mask:0xf bank_mask:0xf
	v_fmamk_f32 v0, v0, 0x3a000000, v186
	v_cmp_gt_f32_e32 vcc, s54, v0
	v_mul_f32_e32 v1, 0x4b800000, v0
	s_nop 0
	v_cndmask_b32_e32 v0, v0, v1, vcc
	v_rsq_f32_e32 v0, v0
	s_nop 0
	v_mul_f32_e32 v1, 0x45800000, v0
	v_cndmask_b32_e32 v52, v0, v1, vcc
	v_pk_mul_f32 v[2:3], v[100:101], v[52:53] op_sel_hi:[1,0]
	v_pk_mul_f32 v[0:1], v[92:93], v[52:53] op_sel_hi:[1,0]
	v_pk_fma_f32 v[82:83], v[122:123], v[2:3], v[130:131]
	v_pk_mul_f32 v[2:3], v[96:97], v[52:53] op_sel_hi:[1,0]
	v_pk_fma_f32 v[0:1], v[114:115], v[0:1], v[126:127]
	v_pk_fma_f32 v[2:3], v[116:117], v[2:3], v[128:129]
	v_pk_mul_f32 v[84:85], v[104:105], v[52:53] op_sel_hi:[1,0]
	v_add_co_u32_e32 v74, vcc, s16, v74
	v_pk_fma_f32 v[84:85], v[124:125], v[84:85], v[132:133]
	global_store_dwordx4 v[46:47], v[0:3], off offset:512
	global_store_dwordx4 v[46:47], v[82:85], off offset:528
	v_addc_co_u32_e32 v75, vcc, 0, v75, vcc
	s_waitcnt vmcnt(2)
	v_pk_fma_f32 v[0:1], v[144:145], v[0:1], v[138:139]
	v_pk_fma_f32 v[2:3], v[146:147], v[2:3], v[140:141]
	v_cvt_pk_bf16_f32 v0, v0, v1
	v_cvt_pk_bf16_f32 v1, v2, v3
	v_pk_fma_f32 v[2:3], v[148:149], v[82:83], v[134:135]
	v_pk_fma_f32 v[82:83], v[150:151], v[84:85], v[136:137]
	v_cvt_pk_bf16_f32 v2, v2, v3
	v_cvt_pk_bf16_f32 v3, v82, v83
	global_store_dwordx4 v[74:75], v[0:3], off offset:512
	global_load_dwordx4 v[0:3], v[20:21], off offset:2064
	s_nop 0
	global_load_dwordx4 v[82:85], v[20:21], off offset:2048
	global_load_dwordx4 v[86:89], v[22:23], off offset:2064
	global_load_dwordx4 v[90:93], v[22:23], off offset:2048
	v_pk_mul_f32 v[72:73], v[72:73], v[52:53] op_sel_hi:[1,0]
	v_pk_mul_f32 v[68:69], v[68:69], v[52:53] op_sel_hi:[1,0]
	v_pk_mul_f32 v[70:71], v[70:71], v[52:53] op_sel_hi:[1,0]
	v_pk_mul_f32 v[66:67], v[66:67], v[52:53] op_sel_hi:[1,0]
	v_pk_mul_f32 v[14:15], v[14:15], v[52:53] op_sel_hi:[1,0]
	v_pk_mul_f32 v[10:11], v[10:11], v[52:53] op_sel_hi:[1,0]
	v_pk_mul_f32 v[12:13], v[12:13], v[52:53] op_sel_hi:[1,0]
	v_pk_mul_f32 v[8:9], v[8:9], v[52:53] op_sel_hi:[1,0]
	s_movk_i32 s16, 0x2fff
	v_cmp_lt_i32_e32 vcc, s16, v18
	s_or_b64 s[14:15], vcc, s[14:15]
	s_waitcnt vmcnt(1)
	v_pk_fma_f32 v[0:1], v[0:1], v[70:71], v[86:87]
	s_waitcnt vmcnt(0)
	v_pk_fma_f32 v[82:83], v[82:83], v[72:73], v[90:91]
	v_pk_fma_f32 v[84:85], v[84:85], v[68:69], v[92:93]
	v_pk_fma_f32 v[2:3], v[2:3], v[66:67], v[88:89]
	global_store_dwordx4 v[46:47], v[82:85], off offset:2560
	global_store_dwordx4 v[46:47], v[0:3], off offset:2576
	global_load_dwordx4 v[66:69], v[64:65], off offset:16
	global_load_dwordx4 v[70:73], v[64:65], off
	global_load_dwordx4 v[86:89], v[60:61], off offset:16
	global_load_dwordx4 v[90:93], v[60:61], off
	s_waitcnt vmcnt(2)
	v_pk_add_f32 v[46:47], v[70:71], 1.0 op_sel_hi:[1,0]
	s_waitcnt vmcnt(0)
	v_pk_fma_f32 v[46:47], v[46:47], v[82:83], v[90:91]
	s_nop 0
	v_cvt_pk_bf16_f32 v64, v46, v47
	v_pk_add_f32 v[46:47], v[72:73], 1.0 op_sel_hi:[1,0]
	s_nop 0
	v_pk_fma_f32 v[46:47], v[46:47], v[84:85], v[92:93]
	s_nop 0
	v_cvt_pk_bf16_f32 v65, v46, v47
	v_pk_add_f32 v[46:47], v[66:67], 1.0 op_sel_hi:[1,0]
	s_nop 0
	v_pk_fma_f32 v[0:1], v[46:47], v[0:1], v[86:87]
	v_pk_mul_f32 v[46:47], v[62:63], v[52:53] op_sel_hi:[1,0]
	v_cvt_pk_bf16_f32 v66, v0, v1
	v_pk_add_f32 v[0:1], v[68:69], 1.0 op_sel_hi:[1,0]
	s_nop 0
	v_pk_fma_f32 v[0:1], v[0:1], v[2:3], v[88:89]
	s_nop 0
	v_cvt_pk_bf16_f32 v67, v0, v1
	global_store_dwordx4 v[74:75], v[64:67], off offset:1536
	global_load_dwordx4 v[0:3], v[24:25], off offset:16
	s_nop 0
	global_load_dwordx4 v[64:67], v[24:25], off
	global_load_dwordx4 v[68:71], v[26:27], off offset:16
	global_load_dwordx4 v[82:85], v[26:27], off
	s_waitcnt vmcnt(0)
	v_pk_fma_f32 v[60:61], v[64:65], v[46:47], v[82:83]
	v_pk_mul_f32 v[46:47], v[58:59], v[52:53] op_sel_hi:[1,0]
	s_nop 0
	v_pk_fma_f32 v[0:1], v[0:1], v[46:47], v[68:69]
	v_pk_mul_f32 v[46:47], v[56:57], v[52:53] op_sel_hi:[1,0]
	s_nop 0
	v_pk_fma_f32 v[62:63], v[66:67], v[46:47], v[84:85]
	v_pk_mul_f32 v[46:47], v[54:55], v[52:53] op_sel_hi:[1,0]
	s_nop 0
	v_pk_fma_f32 v[2:3], v[2:3], v[46:47], v[70:71]
	global_store_dwordx4 v[44:45], v[60:63], off offset:512
	global_store_dwordx4 v[44:45], v[0:3], off offset:528
	global_load_dwordx4 v[54:57], v[50:51], off offset:16
	global_load_dwordx4 v[64:67], v[50:51], off
	global_load_dwordx4 v[68:71], v[48:49], off offset:16
	s_nop 0
	global_load_dwordx4 v[46:49], v[48:49], off
	s_waitcnt vmcnt(2)
	v_pk_add_f32 v[50:51], v[64:65], 1.0 op_sel_hi:[1,0]
	s_waitcnt vmcnt(0)
	v_pk_fma_f32 v[46:47], v[50:51], v[60:61], v[46:47]
	v_pk_add_f32 v[50:51], v[66:67], 1.0 op_sel_hi:[1,0]
	v_cvt_pk_bf16_f32 v46, v46, v47
	v_pk_fma_f32 v[48:49], v[50:51], v[62:63], v[48:49]
	s_nop 0
	v_cvt_pk_bf16_f32 v47, v48, v49
	v_pk_add_f32 v[48:49], v[54:55], 1.0 op_sel_hi:[1,0]
	s_nop 0
	v_pk_fma_f32 v[0:1], v[48:49], v[0:1], v[68:69]
	s_nop 0
	v_cvt_pk_bf16_f32 v48, v0, v1
	v_pk_add_f32 v[0:1], v[56:57], 1.0 op_sel_hi:[1,0]
	s_nop 0
	v_pk_fma_f32 v[0:1], v[0:1], v[2:3], v[70:71]
	s_nop 0
	v_cvt_pk_bf16_f32 v49, v0, v1
	global_store_dwordx4 v[74:75], v[46:49], off offset:2560
	global_load_dwordx4 v[0:3], v[28:29], off offset:16
	s_nop 0
	global_load_dwordx4 v[46:49], v[28:29], off
	global_load_dwordx4 v[54:57], v[30:31], off offset:16
	global_load_dwordx4 v[58:61], v[30:31], off
	s_waitcnt vmcnt(1)
	v_pk_fma_f32 v[0:1], v[0:1], v[12:13], v[54:55]
	s_waitcnt vmcnt(0)
	v_pk_fma_f32 v[46:47], v[46:47], v[14:15], v[58:59]
	v_pk_fma_f32 v[48:49], v[48:49], v[10:11], v[60:61]
	v_pk_fma_f32 v[2:3], v[2:3], v[8:9], v[56:57]
	global_store_dwordx4 v[44:45], v[46:49], off offset:2560
	global_store_dwordx4 v[44:45], v[0:3], off offset:2576
	global_load_dwordx4 v[8:11], v[6:7], off offset:16
	global_load_dwordx4 v[12:15], v[6:7], off
	global_load_dwordx4 v[50:53], v[4:5], off offset:16
	s_nop 0
	global_load_dwordx4 v[4:7], v[4:5], off
	s_waitcnt vmcnt(2)
	v_pk_add_f32 v[12:13], v[12:13], 1.0 op_sel_hi:[1,0]
	s_waitcnt vmcnt(0)
	v_pk_fma_f32 v[4:5], v[12:13], v[46:47], v[4:5]
	v_pk_add_f32 v[12:13], v[14:15], 1.0 op_sel_hi:[1,0]
	v_cvt_pk_bf16_f32 v4, v4, v5
	v_pk_fma_f32 v[6:7], v[12:13], v[48:49], v[6:7]
	s_nop 0
	v_cvt_pk_bf16_f32 v5, v6, v7
	v_pk_add_f32 v[6:7], v[8:9], 1.0 op_sel_hi:[1,0]
	s_nop 0
	v_pk_fma_f32 v[0:1], v[6:7], v[0:1], v[50:51]
	s_nop 0
	v_cvt_pk_bf16_f32 v6, v0, v1
	v_pk_add_f32 v[0:1], v[10:11], 1.0 op_sel_hi:[1,0]
	s_nop 0
	v_pk_fma_f32 v[0:1], v[0:1], v[2:3], v[52:53]
	s_nop 0
	v_cvt_pk_bf16_f32 v7, v0, v1
	global_store_dwordx4 v[74:75], v[4:7], off offset:3584
	s_andn2_b64 exec, exec, s[14:15]
	s_cbranch_execnz .LBB0_589
